# v34 + out phase (retention, GLA items): second MFMA chain's operand loads issued before the first chain's loads (spare registers) so both latencies overlap
# baseline (speedup 1.0000x reference)
; DI int crow(int i, int hh) { return (i & 3) + 8 * (i >> 2) + 4 * hh; }
; #define MFMA32(a, b, c) __builtin_amdgcn_mfma_f32_32x32x16_bf16((a), (b), (c), 0, 0, 0)
; template <int BR> DI void out_item(PARAMS P, int l, int cid, int h, LAS unsigned char* lds, int wave, int lane) {
;     ...
;     f32x16 o;
; #pragma unroll
;     for (int i = 0; i < 16; ++i) o[i] = 0.f;
; #pragma unroll
;     for (int ks = 0; ks < NKS; ++ks) {
;         const bf16x8 a = *(const bf16x8*)(Q + (size_t)(32 * tt + r) * QW + 16 * ks + 8 * hh);
;         typedef short s16x4_o __attribute__((ext_vector_type(4)));
;         const bf16_t* stp = ST + (size_t)((((ks >> 1) * 4 + 2 * (ks & 1) + hh) * 2) * 128 + 32 * vt + r) * 4;
;         const s16x4_o b0_ = *(const s16x4_o*)stp, b1_ = *(const s16x4_o*)(stp + 512);
;         const bf16x8 b = __builtin_shufflevector(b0_, b1_, 0, 1, 2, 3, 4, 5, 6, 7);
;         o = MFMA32(a, b, o);
;     }
;     if (BR == 1) {
; #pragma unroll
;         for (int i = 0; i < 16; ++i) o[i] *= __expf(mp - fmaxf(mp, Gl[32 * tt + crow(i, hh)]));
;     }
;     if (wave < 4) {
;         const int ts = wave >> 1, ss = wave & 1; f32x16 p;
; #pragma unroll
;         for (int i = 0; i < 16; ++i) p[i] = 0.f;
;         if (ss <= ts) {
; #pragma unroll
;             for (int ks = 0; ks < NKS; ++ks) {
;                 const bf16x8 a = *(const bf16x8*)(Q + (size_t)(32 * ts + r) * QW + 16 * ks + 8 * hh), b = *(const bf16x8*)(K + (size_t)(32 * ss + r) * QW + 16 * ks + 8 * hh);
;                 p = MFMA32(a, b, p);
;             }
;         }
.LBB0_510:
	v_cndmask_b32_e64 v0, 0, 1, s[40:41]
	s_andn2_b64 vcc, exec, s[6:7]
	v_lshlrev_b32_e32 v32, 1, v52
	v_cmp_ne_u32_e64 s[8:9], 1, v0
	s_cbranch_vccnz .LBB0_516
	s_lshl_b32 s6, s68, 2
	s_or_b32 s6, s6, s3
	s_ashr_i32 s7, s6, 31
	s_lshl_b64 s[16:17], s[6:7], 14
	s_lshl_b64 s[6:7], s[56:57], 9
	s_add_u32 s6, s60, s6
	s_addc_u32 s7, s61, s7
	s_lshl_b32 s12, s3, 7
	s_add_u32 s6, s6, s12
	s_addc_u32 s7, s7, 0
	s_and_b64 vcc, exec, s[8:9]
	s_cbranch_vccnz .Lob2_skip
	s_andn2_b64 vcc, exec, s[44:45]
	s_cbranch_vccnz .Lob2_skip
	s_lshl_b64 s[98:99], s[56:57], 9
	v_readlane_b32 s100, v252, 2
	s_add_u32 s98, s100, s98
	v_readlane_b32 s100, v252, 3
	s_addc_u32 s99, s100, s99
	s_lshl_b32 s100, s3, 7
	s_add_u32 s98, s98, s100
	s_addc_u32 s99, s99, 0
	v_lshl_add_u64 v[204:205], s[6:7], 0, v[66:67]
	v_lshlrev_b32_e32 v206, 1, v62
	v_mov_b32_e32 v207, v33
	v_lshl_add_u64 v[204:205], v[204:205], 0, v[32:33]
	v_lshl_add_u64 v[206:207], s[98:99], 0, v[206:207]
	v_lshl_add_u64 v[206:207], v[206:207], 0, v[32:33]
	global_load_dwordx4 v[170:173], v[204:205], off
	global_load_dwordx4 v[174:177], v[206:207], off
	global_load_dwordx4 v[178:181], v[204:205], off offset:32
	global_load_dwordx4 v[182:185], v[206:207], off offset:32
	global_load_dwordx4 v[186:189], v[204:205], off offset:64
	global_load_dwordx4 v[190:193], v[206:207], off offset:64
	global_load_dwordx4 v[208:211], v[204:205], off offset:96
	global_load_dwordx4 v[212:215], v[206:207], off offset:96
.Lob2_skip:
	v_lshl_add_u64 v[0:1], s[6:7], 0, v[64:65]
	v_mov_b32_e32 v34, v228
	v_lshl_add_u64 v[24:25], v[0:1], 0, v[32:33]
	global_load_dwordx4 v[0:3], v[24:25], off
	v_lshl_add_u64 v[26:27], v[68:69], 0, s[16:17]
	global_load_dwordx2 v[4:5], v[26:27], off
	global_load_dwordx2 v[6:7], v[26:27], off offset:1024
	global_load_dwordx4 v[16:19], v[24:25], off offset:32
	v_add_co_u32_e32 v28, vcc, 0x2000, v26
	s_nop 1
	v_addc_co_u32_e32 v29, vcc, 0, v27, vcc
	v_add_co_u32_e32 v126, vcc, 0x3000, v26
	s_nop 1
	v_addc_co_u32_e32 v127, vcc, 0, v27, vcc
	global_load_dwordx2 v[20:21], v[28:29], off offset:-4096
	global_load_dwordx2 v[22:23], v[28:29], off offset:-3072
	global_load_dwordx4 v[112:115], v[24:25], off offset:64
	global_load_dwordx2 v[116:117], v[126:127], off offset:-4096
	global_load_dwordx2 v[118:119], v[126:127], off offset:-3072
	global_load_dwordx4 v[120:123], v[24:25], off offset:96
	global_load_dwordx2 v[124:125], v[126:127], off
	global_load_dwordx2 v[126:127], v[126:127], off offset:1024
	s_waitcnt vmcnt(9)
	v_mfma_f32_32x32x16_bf16 v[0:15], v[0:3], v[4:7], 0
	s_waitcnt vmcnt(6)
	v_mfma_f32_32x32x16_bf16 v[0:15], v[16:19], v[20:23], v[0:15]
	s_waitcnt vmcnt(3)
	v_mfma_f32_32x32x16_bf16 v[0:15], v[112:115], v[116:119], v[0:15]
	s_waitcnt vmcnt(0)
	v_mfma_f32_32x32x16_bf16 v[0:15], v[120:123], v[124:127], v[0:15]
	s_and_b64 vcc, exec, s[8:9]
	s_cbranch_vccnz .LBB0_515
	v_mov_b32_e32 v16, 0
	s_andn2_b64 vcc, exec, s[44:45]
	v_mov_b32_e32 v17, 0
	v_mov_b32_e32 v18, 0
	v_mov_b32_e32 v19, 0
	v_mov_b32_e32 v20, 0
	v_mov_b32_e32 v21, 0
	v_mov_b32_e32 v22, 0
	v_mov_b32_e32 v23, 0
	v_mov_b32_e32 v24, 0
	v_mov_b32_e32 v25, 0
	v_mov_b32_e32 v26, 0
	v_mov_b32_e32 v27, 0
	v_mov_b32_e32 v28, 0
	v_mov_b32_e32 v29, 0
	v_mov_b32_e32 v30, 0
	v_mov_b32_e32 v31, 0
	s_cbranch_vccnz .LBB0_514
	v_mfma_f32_32x32x16_bf16 v[16:31], v[170:173], v[174:177], 0
	v_mfma_f32_32x32x16_bf16 v[16:31], v[178:181], v[182:185], v[16:31]
	v_mfma_f32_32x32x16_bf16 v[16:31], v[186:189], v[190:193], v[16:31]
	v_mfma_f32_32x32x16_bf16 v[16:31], v[208:211], v[212:215], v[16:31]

; DI int crow(int i, int hh) { return (i & 3) + 8 * (i >> 2) + 4 * hh; }
; #define MFMA32(a, b, c) __builtin_amdgcn_mfma_f32_32x32x16_bf16((a), (b), (c), 0, 0, 0)
; template <int BR> DI void out_item(PARAMS P, int l, int cid, int h, LAS unsigned char* lds, int wave, int lane) {
;     ...
;     f32x16 o;
; #pragma unroll
;     for (int i = 0; i < 16; ++i) o[i] = 0.f;
; #pragma unroll
;     for (int ks = 0; ks < NKS; ++ks) {
;         const bf16x8 a = *(const bf16x8*)(Q + (size_t)(32 * tt + r) * QW + 16 * ks + 8 * hh);
;         typedef short s16x4_o __attribute__((ext_vector_type(4)));
;         const bf16_t* stp = ST + (size_t)((((ks >> 1) * 4 + 2 * (ks & 1) + hh) * 2) * 128 + 32 * vt + r) * 4;
;         const s16x4_o b0_ = *(const s16x4_o*)stp, b1_ = *(const s16x4_o*)(stp + 512);
;         const bf16x8 b = __builtin_shufflevector(b0_, b1_, 0, 1, 2, 3, 4, 5, 6, 7);
;         o = MFMA32(a, b, o);
;     }
;     if (BR == 1) {
; #pragma unroll
;         for (int i = 0; i < 16; ++i) o[i] *= __expf(mp - fmaxf(mp, Gl[32 * tt + crow(i, hh)]));
;     }
;     if (wave < 4) {
;         const int ts = wave >> 1, ss = wave & 1; f32x16 p;
; #pragma unroll
;         for (int i = 0; i < 16; ++i) p[i] = 0.f;
;         if (ss <= ts) {
; #pragma unroll
;             for (int ks = 0; ks < NKS; ++ks) {
;                 const bf16x8 a = *(const bf16x8*)(Q + (size_t)(32 * ts + r) * QW + 16 * ks + 8 * hh), b = *(const bf16x8*)(K + (size_t)(32 * ss + r) * QW + 16 * ks + 8 * hh);
;                 p = MFMA32(a, b, p);
;             }
;         }
.LBB0_516:
	s_and_b64 vcc, exec, s[16:17]
	s_cbranch_vccz .LBB0_465
	s_lshl_b32 s6, s68, 2
	s_or_b32 s6, s6, s3
	s_ashr_i32 s7, s6, 31
	s_lshl_b64 s[16:17], s[6:7], 14
	s_lshl_b64 s[6:7], s[56:57], 9
	s_add_u32 s6, s69, s6
	s_addc_u32 s7, s72, s7
	s_lshl_b32 s12, s3, 7
	s_add_u32 s6, s6, s12
	s_addc_u32 s7, s7, 0
	s_and_b64 vcc, exec, s[8:9]
	s_cbranch_vccnz .Lob0_skip
	s_andn2_b64 vcc, exec, s[44:45]
	s_cbranch_vccnz .Lob0_skip
	s_lshl_b64 s[98:99], s[56:57], 9
	v_readlane_b32 s100, v252, 0
	s_add_u32 s98, s100, s98
	v_readlane_b32 s100, v252, 1
	s_addc_u32 s99, s100, s99
	s_lshl_b32 s100, s3, 7
	s_add_u32 s98, s98, s100
	s_addc_u32 s99, s99, 0
	v_lshl_add_u64 v[204:205], s[6:7], 0, v[66:67]
	v_lshlrev_b32_e32 v206, 1, v62
	v_mov_b32_e32 v207, v33
	v_lshl_add_u64 v[204:205], v[204:205], 0, v[32:33]
	v_lshl_add_u64 v[206:207], s[98:99], 0, v[206:207]
	v_lshl_add_u64 v[206:207], v[206:207], 0, v[32:33]
	global_load_dwordx4 v[170:173], v[204:205], off
	global_load_dwordx4 v[174:177], v[206:207], off
	global_load_dwordx4 v[178:181], v[204:205], off offset:32
	global_load_dwordx4 v[182:185], v[206:207], off offset:32
	global_load_dwordx4 v[186:189], v[204:205], off offset:64
	global_load_dwordx4 v[190:193], v[206:207], off offset:64
	global_load_dwordx4 v[208:211], v[204:205], off offset:96
	global_load_dwordx4 v[212:215], v[206:207], off offset:96
.Lob0_skip:
	v_lshl_add_u64 v[0:1], s[6:7], 0, v[64:65]
	v_mov_b32_e32 v34, v228
	v_lshl_add_u64 v[24:25], v[0:1], 0, v[32:33]
	global_load_dwordx4 v[0:3], v[24:25], off
	v_lshl_add_u64 v[26:27], v[54:55], 0, s[16:17]
	global_load_dwordx2 v[4:5], v[26:27], off
	global_load_dwordx2 v[6:7], v[26:27], off offset:1024
	global_load_dwordx4 v[16:19], v[24:25], off offset:32
	v_add_co_u32_e32 v28, vcc, 0x2000, v26
	s_nop 1
	v_addc_co_u32_e32 v29, vcc, 0, v27, vcc
	v_add_co_u32_e32 v126, vcc, 0x3000, v26
	s_nop 1
	v_addc_co_u32_e32 v127, vcc, 0, v27, vcc
	global_load_dwordx2 v[20:21], v[28:29], off offset:-4096
	global_load_dwordx2 v[22:23], v[28:29], off offset:-3072
	global_load_dwordx4 v[112:115], v[24:25], off offset:64
	global_load_dwordx2 v[116:117], v[126:127], off offset:-4096
	global_load_dwordx2 v[118:119], v[126:127], off offset:-3072
	global_load_dwordx4 v[120:123], v[24:25], off offset:96
	global_load_dwordx2 v[124:125], v[126:127], off
	global_load_dwordx2 v[126:127], v[126:127], off offset:1024
	s_waitcnt vmcnt(9)
	v_mfma_f32_32x32x16_bf16 v[0:15], v[0:3], v[4:7], 0
	s_waitcnt vmcnt(6)
	v_mfma_f32_32x32x16_bf16 v[0:15], v[16:19], v[20:23], v[0:15]
	s_waitcnt vmcnt(3)
	v_mfma_f32_32x32x16_bf16 v[0:15], v[112:115], v[116:119], v[0:15]
	s_waitcnt vmcnt(0)
	v_mfma_f32_32x32x16_bf16 v[0:15], v[120:123], v[124:127], v[0:15]
	s_and_b64 vcc, exec, s[8:9]
	s_cbranch_vccnz .LBB0_464
	v_mov_b32_e32 v16, 0
	s_andn2_b64 vcc, exec, s[44:45]
	v_mov_b32_e32 v17, 0
	v_mov_b32_e32 v18, 0
	v_mov_b32_e32 v19, 0
	v_mov_b32_e32 v20, 0
	v_mov_b32_e32 v21, 0
	v_mov_b32_e32 v22, 0
	v_mov_b32_e32 v23, 0
	v_mov_b32_e32 v24, 0
	v_mov_b32_e32 v25, 0
	v_mov_b32_e32 v26, 0
	v_mov_b32_e32 v27, 0
	v_mov_b32_e32 v28, 0
	v_mov_b32_e32 v29, 0
	v_mov_b32_e32 v30, 0
	v_mov_b32_e32 v31, 0
	s_cbranch_vccnz .LBB0_463
	v_mfma_f32_32x32x16_bf16 v[16:31], v[170:173], v[174:177], 0
	v_mfma_f32_32x32x16_bf16 v[16:31], v[178:181], v[182:185], v[16:31]
	v_mfma_f32_32x32x16_bf16 v[16:31], v[186:189], v[190:193], v[16:31]
	v_mfma_f32_32x32x16_bf16 v[16:31], v[208:211], v[212:215], v[16:31]
	s_branch .LBB0_463
